# NSA in-projection epilogue: the eight per-row-block row-sum loads issued together (one round trip instead of eight), later code placement kept identical mod 64
# baseline (speedup 1.0000x reference)
; __device__ __forceinline__ unsigned xb_ld(unsigned* p)              { return __hip_atomic_load(p, __ATOMIC_RELAXED, __HIP_MEMORY_SCOPE_AGENT); }
; __device__ __forceinline__ unsigned xb_add(unsigned* p, unsigned v) { return __hip_atomic_fetch_add(p, v, __ATOMIC_RELAXED, __HIP_MEMORY_SCOPE_AGENT); }
; #define XB_SPIN(cond) do { unsigned _sp = 0; while (cond) { __builtin_amdgcn_s_sleep(1); if (++_sp > (1u << 24)) break; } } while (0)
; __device__ __forceinline__ void grid_barrier(unsigned* bar, volatile LAS unsigned* st, unsigned k) {
;     ...
;       else XB_SPIN(xb_ld(&bar[XB_TOPGEN]) == k);
;       __builtin_amdgcn_fence(__ATOMIC_ACQUIRE, "agent");
;       xb_add(&bar[XB_XGEN(x)], 1u);
;       asm volatile("s_waitcnt vmcnt(0)" ::: "memory");
;     } else {
;       XB_SPIN(xb_ld(&bar[XB_XGEN(x)]) == k);
;       __builtin_amdgcn_fence(__ATOMIC_ACQUIRE, "agent");
;       asm volatile("s_waitcnt vmcnt(0)" ::: "memory");
.LBB0_873:
	global_load_dword v1, v0, s[6:7] sc1
	s_mov_b64 s[10:11], -1
	s_waitcnt vmcnt(0)
	v_cmp_ne_u32_e32 vcc, s33, v1
	s_cbranch_vccnz .LBB0_872
	s_cmp_lg_u32 s12, 0
	s_sleep 1
	s_cbranch_scc0 .LBB0_871
	global_load_dword v1, v0, s[6:7] sc1
	s_waitcnt vmcnt(0)
	v_cmp_eq_u32_e32 vcc, s33, v1
	s_cbranch_vccz .LBB0_872
	s_sleep 1
	global_load_dword v1, v0, s[6:7] sc1
	s_waitcnt vmcnt(0)
	v_cmp_eq_u32_e32 vcc, s33, v1
	s_cbranch_vccz .LBB0_872
	s_sleep 1
	global_load_dword v1, v0, s[6:7] sc1
	s_waitcnt vmcnt(0)
	v_cmp_eq_u32_e32 vcc, s33, v1
	s_cbranch_vccz .LBB0_872
	s_sleep 1
	global_load_dword v1, v0, s[6:7] sc1
	s_waitcnt vmcnt(0)
	v_cmp_eq_u32_e32 vcc, s33, v1
	s_cbranch_vccz .LBB0_872
	s_sleep 1
	global_load_dword v1, v0, s[6:7] sc1
	s_waitcnt vmcnt(0)
	v_cmp_eq_u32_e32 vcc, s33, v1
	s_cbranch_vccz .LBB0_872
	s_sleep 1
	global_load_dword v1, v0, s[6:7] sc1
	s_waitcnt vmcnt(0)
	v_cmp_eq_u32_e32 vcc, s33, v1
	s_cbranch_vccz .LBB0_872
	s_sleep 1
	global_load_dword v1, v0, s[6:7] sc1
	s_waitcnt vmcnt(0)
	v_cmp_eq_u32_e32 vcc, s33, v1
	s_cbranch_vccz .LBB0_872
	s_sleep 1
	s_add_i32 s12, s12, -8
	s_mov_b64 s[10:11], 0
	s_branch .LBB0_872
	s_nop 0
	s_nop 0
	s_nop 0
	s_nop 0
	s_nop 0
	s_nop 0
	s_nop 0
	s_nop 0
	s_nop 0
